# phase-0 x copy remapped to one contiguous 128 KiB slab per workgroup and input, unrolled x4 with 8 loads in flight (256-workgroup grid only; original loop kept for other grids)
# baseline (speedup 1.0000x reference)
.LBB0_1073:
	s_waitcnt vmcnt(0)
	v_mov_b32_e32 v0, v192
	s_mov_b64 s[0:1], 0x200000
	v_ashrrev_i32_e32 v1, 31, v0
	v_lshl_add_u64 v[2:3], s[82:83], 0, v[0:1]
	v_cmp_gt_u64_e32 vcc, s[0:1], v[2:3]
	s_and_saveexec_b64 s[6:7], vcc
	v_readlane_b32 s4, v253, 11
	v_readlane_b32 s10, v253, 13
	v_readlane_b32 s12, v253, 24
	v_readlane_b32 s5, v253, 12
	v_readlane_b32 s11, v253, 14
	v_readlane_b32 s13, v253, 25
	v_readlane_b32 s14, v253, 26
	v_readlane_b32 s15, v253, 27
	v_readlane_b32 s16, v253, 28
	v_readlane_b32 s17, v253, 29
	v_readlane_b32 s18, v253, 30
	v_readlane_b32 s19, v253, 31
	v_readlane_b32 s20, v253, 32
	v_readlane_b32 s21, v253, 33
	v_readlane_b32 s22, v253, 34
	v_readlane_b32 s23, v253, 35
	v_readlane_b32 s24, v253, 36
	v_readlane_b32 s25, v253, 37
	v_readlane_b32 s26, v253, 38
	v_readlane_b32 s27, v253, 39
	s_cbranch_execz .LBB0_1076
	v_readlane_b32 s0, v252, 43
	s_add_u32 s0, s62, s0
	v_readlane_b32 s1, v252, 44
	s_addc_u32 s1, s63, s1
	s_mov_b64 s[8:9], 0
	v_lshl_add_u64 v[4:5], v[0:1], 3, s[0:1]
	v_readlane_b32 s0, v252, 45
	v_readlane_b32 s1, v252, 46
	v_mov_b64_e32 v[8:9], v[2:3]
	s_nop 0
	v_lshl_add_u64 v[6:7], v[0:1], 4, s[0:1]
	s_cmp_eq_u32 s38, 0x20000
	s_cbranch_scc0 .Lxc_generic
	s_lshl_b32 s0, s2, 16
	s_add_u32 s0, s0, 0x3000000
	s_mov_b32 s1, 0
	s_add_u32 s0, s62, s0
	s_addc_u32 s1, s63, s1
	v_lshl_add_u64 v[4:5], v[0:1], 3, s[0:1]
	s_lshl_b32 s0, s2, 17
	s_mov_b32 s1, 0
	v_lshl_add_u64 v[6:7], v[0:1], 4, s[0:1]
	s_movk_i32 s4, 0x1000
	s_mov_b32 s5, 0
	s_movk_i32 s10, 0x2000
	s_mov_b32 s11, 0
	s_mov_b32 s8, 4
.Lxc_fast:
	v_lshl_add_u64 v[10:11], s[12:13], 0, v[6:7]
	v_lshl_add_u64 v[14:15], s[14:15], 0, v[6:7]
	global_load_dwordx4 v[214:217], v[10:11], off
	global_load_dwordx4 v[218:221], v[14:15], off
	v_lshl_add_u64 v[6:7], v[6:7], 0, s[10:11]
	v_lshl_add_u64 v[10:11], s[12:13], 0, v[6:7]
	v_lshl_add_u64 v[14:15], s[14:15], 0, v[6:7]
	global_load_dwordx4 v[222:225], v[10:11], off
	global_load_dwordx4 v[226:229], v[14:15], off
	v_lshl_add_u64 v[6:7], v[6:7], 0, s[10:11]
	v_lshl_add_u64 v[10:11], s[12:13], 0, v[6:7]
	v_lshl_add_u64 v[14:15], s[14:15], 0, v[6:7]
	global_load_dwordx4 v[230:233], v[10:11], off
	global_load_dwordx4 v[234:237], v[14:15], off
	v_lshl_add_u64 v[6:7], v[6:7], 0, s[10:11]
	v_lshl_add_u64 v[10:11], s[12:13], 0, v[6:7]
	v_lshl_add_u64 v[14:15], s[14:15], 0, v[6:7]
	global_load_dwordx4 v[238:241], v[10:11], off
	global_load_dwordx4 v[242:245], v[14:15], off
	v_lshl_add_u64 v[6:7], v[6:7], 0, s[10:11]
	s_waitcnt vmcnt(6)
	v_cvt_pk_bf16_f32 v10, v214, v215
	v_cvt_pk_bf16_f32 v11, v216, v217
	v_cvt_pk_bf16_f32 v12, v218, v219
	v_cvt_pk_bf16_f32 v13, v220, v221
	v_add_co_u32_e32 v18, vcc, 0xff000000, v4
	s_nop 1
	v_addc_co_u32_e32 v19, vcc, -1, v5, vcc
	global_store_dwordx2 v[18:19], v[10:11], off
	global_store_dwordx2 v[4:5], v[12:13], off
	v_lshl_add_u64 v[4:5], v[4:5], 0, s[4:5]
	s_waitcnt vmcnt(6)
	v_cvt_pk_bf16_f32 v10, v222, v223
	v_cvt_pk_bf16_f32 v11, v224, v225
	v_cvt_pk_bf16_f32 v12, v226, v227
	v_cvt_pk_bf16_f32 v13, v228, v229
	v_add_co_u32_e32 v18, vcc, 0xff000000, v4
	s_nop 1
	v_addc_co_u32_e32 v19, vcc, -1, v5, vcc
	global_store_dwordx2 v[18:19], v[10:11], off
	global_store_dwordx2 v[4:5], v[12:13], off
	v_lshl_add_u64 v[4:5], v[4:5], 0, s[4:5]
	s_waitcnt vmcnt(6)
	v_cvt_pk_bf16_f32 v10, v230, v231
	v_cvt_pk_bf16_f32 v11, v232, v233
	v_cvt_pk_bf16_f32 v12, v234, v235
	v_cvt_pk_bf16_f32 v13, v236, v237
	v_add_co_u32_e32 v18, vcc, 0xff000000, v4
	s_nop 1
	v_addc_co_u32_e32 v19, vcc, -1, v5, vcc
	global_store_dwordx2 v[18:19], v[10:11], off
	global_store_dwordx2 v[4:5], v[12:13], off
	v_lshl_add_u64 v[4:5], v[4:5], 0, s[4:5]
	s_waitcnt vmcnt(6)
	v_cvt_pk_bf16_f32 v10, v238, v239
	v_cvt_pk_bf16_f32 v11, v240, v241
	v_cvt_pk_bf16_f32 v12, v242, v243
	v_cvt_pk_bf16_f32 v13, v244, v245
	v_add_co_u32_e32 v18, vcc, 0xff000000, v4
	s_nop 1
	v_addc_co_u32_e32 v19, vcc, -1, v5, vcc
	global_store_dwordx2 v[18:19], v[10:11], off
	global_store_dwordx2 v[4:5], v[12:13], off
	v_lshl_add_u64 v[4:5], v[4:5], 0, s[4:5]
	s_sub_i32 s8, s8, 1
	s_cmp_lg_u32 s8, 0
	s_cbranch_scc1 .Lxc_fast
	v_readlane_b32 s4, v253, 11
	v_readlane_b32 s5, v253, 12
	v_readlane_b32 s10, v253, 13
	v_readlane_b32 s11, v253, 14
	s_branch .LBB0_1076
